# memory-V transposes also spread over workgroups (one wave each) instead of eight waves on the first eight workgroups
# speedup vs baseline: 1.0127x; 1.0040x over previous
; __global__ void __launch_bounds__(512, 2) fwd_megakernel(Args args) {
;     ...
;             for (int it = gw; it < 64; it += NGW) {
;                 const int bh = it >> 2, tt = it & 3, b = bh >> 2, hh = bh & 3;
;                 transpose64x128(MKV + ((size_t)b * 256 + 64 * tt) * 1024 + 512 + hh * 128, 1024, MVT + (size_t)bh * 128 * 256 + 64 * tt, 256, lane);
.LBB0_557:
	s_mul_i32 s8, s9, s66
	s_add_i32 s8, s8, s86
	s_cmp_gt_i32 s8, 63
	s_movk_i32 s10, 0x6000
	s_mov_b32 s11, 0x8000
	s_mov_b32 s16, 0xa000
	s_mov_b32 s17, 0xc000
	s_mov_b32 s18, 0xe000
	s_cbranch_scc1 .LBB0_560
	s_add_u32 s0, s44, 0x23d00000
	s_addc_u32 s1, s45, 0
	v_lshlrev_b32_e32 v0, 10, v64
	s_lshl_b32 s2, s8, 6
	s_nop 0
	v_lshlrev_b32_e32 v160, 1, v0
	v_lshlrev_b32_e32 v28, 1, v64
